# v20 without the half-1 vmcnt ladder (single vmcnt(0)); keeps the v_lshl_add_u64 staging address math
# baseline (speedup 1.0000x reference)
; __device__ __forceinline__ void finishSM(f32x16& p0, f32x16& p1, float alpha, float& l_reg, bf16x8& pa0, bf16x8& pa1, bf16x8& pa2, bf16x8& pa3) {
; #pragma unroll
;   for (int r = 0; r < 16; ++r) p1[r] = __builtin_amdgcn_exp2f(p1[r]);
;   float ps = 0;
; #pragma unroll
;   for (int r = 0; r < 16; ++r) ps += p0[r];
; #pragma unroll
;   for (int r = 0; r < 16; ++r) ps += p1[r];
;   { auto rr = __builtin_amdgcn_permlane32_swap(__float_as_uint(ps), __float_as_uint(ps), false, false);
;     ps = __uint_as_float(rr[0]) + __uint_as_float(rr[1]); }
;   l_reg = l_reg * alpha + ps;
;     ...
;   PK4(p0, 0, pa0); PK4(p0, 8, pa1); PK4(p1, 0, pa2); PK4(p1, 8, pa3);
;     ...
; }
; __device__ __forceinline__ void qkt(f32x16& p0, f32x16& p1, const char* Ks, const bf16x8* qr, const char* qrl, int r32, int hi) {
;   p0 = f32x16{}; p1 = f32x16{};
; #pragma unroll
;   for (int d0 = 0; d0 < 8; ++d0) { int cb = (d0 * 16 + hi * 8) * 2;
;     bf16x8 b0 = *reinterpret_cast<const bf16x8*>(Ks + KSWZ(r32, cb));
;     bf16x8 b1 = *reinterpret_cast<const bf16x8*>(Ks + KSWZ(32 + r32, cb));
;     p0 = __builtin_amdgcn_mfma_f32_32x32x16_bf16(b0, qr[d0], p0, 0, 0, 0);
;     p1 = __builtin_amdgcn_mfma_f32_32x32x16_bf16(b1, qr[d0], p1, 0, 0, 0); }
; #pragma unroll
;   for (int d0 = 8; d0 < 12; ++d0) { int cb = (d0 * 16 + hi * 8) * 2;
;     bf16x8 b0 = *reinterpret_cast<const bf16x8*>(Ks + KSWZ(r32, cb));
;     bf16x8 b1 = *reinterpret_cast<const bf16x8*>(Ks + KSWZ(32 + r32, cb));
;     bf16x8 qf = *reinterpret_cast<const bf16x8*>(qrl + (((2 * (d0 - 8) + hi) ^ ((r32 >> 1) & 7)) << 4));
;     p0 = __builtin_amdgcn_mfma_f32_32x32x16_bf16(b0, qf, p0, 0, 0, 0);
;     p1 = __builtin_amdgcn_mfma_f32_32x32x16_bf16(b1, qf, p1, 0, 0, 0); }
; }
.Lattn_steady:
	v_exp_f32_e32 v225, v225
	v_exp_f32_e32 v228, v228
	v_exp_f32_e32 v226, v226
	v_add_f32_e32 v211, v225, v228
	s_waitcnt lgkmcnt(3)
	v_mfma_f32_32x32x16_bf16 v[80:95], v[236:239], v[124:127], 0
	ds_read_b128 v[236:239], v206 offset:49152
	v_exp_f32_e32 v229, v229
	v_add_f32_e32 v211, v226, v211
	v_exp_f32_e32 v227, v227
	v_add_f32_e32 v211, v229, v211
	v_mfma_f32_32x32x16_bf16 v[64:79], v[240:243], v[124:127], 0
	ds_read_b128 v[240:243], v208 offset:36864
	v_exp_f32_e32 v230, v230
	v_add_f32_e32 v211, v227, v211
	v_exp_f32_e32 v223, v223
	v_add_f32_e32 v211, v230, v211
	s_waitcnt lgkmcnt(3)
	v_mfma_f32_32x32x16_bf16 v[80:95], v[248:251], v[120:123], v[80:95]
	ds_read_b128 v[248:251], v208 offset:49152
	v_exp_f32_e32 v224, v224
	v_add_f32_e32 v211, v223, v211
	v_exp_f32_e32 v219, v219
	v_add_f32_e32 v211, v224, v211
	v_mfma_f32_32x32x16_bf16 v[64:79], v[244:247], v[120:123], v[64:79]
	ds_read_b128 v[244:247], v207 offset:36864
	v_exp_f32_e32 v221, v221
	v_add_f32_e32 v211, v219, v211
	v_exp_f32_e32 v220, v220
	v_add_f32_e32 v211, v221, v211
	s_waitcnt lgkmcnt(3)
	v_mfma_f32_32x32x16_bf16 v[80:95], v[232:235], v[116:119], v[80:95]
	ds_read_b128 v[232:235], v207 offset:49152
	v_exp_f32_e32 v222, v222
	v_add_f32_e32 v211, v220, v211
	v_exp_f32_e32 v215, v215
	v_add_f32_e32 v211, v222, v211
	v_mfma_f32_32x32x16_bf16 v[64:79], v[236:239], v[116:119], v[64:79]
	ds_read_b128 v[236:239], v204 offset:36864
	v_exp_f32_e32 v217, v217
	v_add_f32_e32 v211, v215, v211
	v_exp_f32_e32 v216, v216
	v_add_f32_e32 v211, v217, v211
	s_waitcnt lgkmcnt(3)
	v_mfma_f32_32x32x16_bf16 v[80:95], v[240:243], v[112:115], v[80:95]
	ds_read_b128 v[240:243], v204 offset:49152
	v_exp_f32_e32 v218, v218
	v_add_f32_e32 v211, v216, v211
	v_exp_f32_e32 v162, v162
	v_add_f32_e32 v211, v218, v211
	v_mfma_f32_32x32x16_bf16 v[64:79], v[248:251], v[112:115], v[64:79]
	ds_read_b128 v[248:251], v203 offset:36864
	v_exp_f32_e32 v163, v163
	v_exp_f32_e32 v160, v160
	v_exp_f32_e32 v161, v161
	s_waitcnt lgkmcnt(3)
	v_mfma_f32_32x32x16_bf16 v[80:95], v[244:247], v[108:111], v[80:95]
	ds_read_b128 v[244:247], v203 offset:49152
	v_exp_f32_e32 v158, v158
	v_exp_f32_e32 v159, v159
	v_exp_f32_e32 v156, v156
	v_mfma_f32_32x32x16_bf16 v[64:79], v[232:235], v[108:111], v[64:79]
	ds_read_b128 v[232:235], v200 offset:36864
	v_exp_f32_e32 v157, v157
	v_exp_f32_e32 v154, v154
	v_exp_f32_e32 v155, v155
	s_waitcnt lgkmcnt(3)
	v_mfma_f32_32x32x16_bf16 v[80:95], v[236:239], v[104:107], v[80:95]
	ds_read_b128 v[236:239], v200 offset:49152
	v_exp_f32_e32 v152, v152
	v_exp_f32_e32 v153, v153
	v_exp_f32_e32 v150, v150
	v_mfma_f32_32x32x16_bf16 v[64:79], v[240:243], v[104:107], v[64:79]
	ds_read_b128 v[240:243], v191 offset:36864
	v_exp_f32_e32 v151, v151
	v_exp_f32_e32 v148, v148
	v_exp_f32_e32 v149, v149
	s_waitcnt lgkmcnt(3)
	v_mfma_f32_32x32x16_bf16 v[80:95], v[248:251], v[100:103], v[80:95]
	ds_read_b128 v[248:251], v202 offset:49152
	v_add_f32_e32 v212, v162, v163
	v_add_f32_e32 v212, v160, v212
	v_add_f32_e32 v212, v161, v212
	v_add_f32_e32 v212, v158, v212
	v_add_f32_e32 v212, v159, v212
	v_add_f32_e32 v212, v156, v212
	v_mfma_f32_32x32x16_bf16 v[64:79], v[244:247], v[100:103], v[64:79]
	ds_read_b128 v[244:247], v182
	v_add_f32_e32 v212, v157, v212
	v_add_f32_e32 v212, v154, v212
	v_add_f32_e32 v212, v155, v212
	v_add_f32_e32 v212, v152, v212
	v_add_f32_e32 v212, v153, v212
	v_add_f32_e32 v212, v150, v212
	s_waitcnt lgkmcnt(3)
	v_mfma_f32_32x32x16_bf16 v[80:95], v[232:235], v[96:99], v[80:95]
	ds_read_b128 v[232:235], v198 offset:36864
	v_add_f32_e32 v212, v151, v212
	v_add_f32_e32 v212, v148, v212
	v_add_f32_e32 v212, v149, v212
	v_add_f32_e32 v211, v211, v212
	v_mov_b32_e32 v212, v211
	s_lshl_b32 s19, s18, 14
	v_add_u32_e32 v231, s19, v183
	s_waitcnt vmcnt(0)
	v_mfma_f32_32x32x16_bf16 v[64:79], v[236:239], v[96:99], v[64:79]
	ds_read_b128 v[236:239], v201 offset:49152
	ds_write_b128 v231, v[140:143]
	v_add_u32_e32 v140, s19, v184
	ds_write_b128 v140, v[144:147]
	ds_write_b128 v185, v[136:139] offset:12288
	ds_write_b128 v185, v[132:135] offset:24576
	s_mov_b32 s18, 0xfffa0000
	ds_write_b128 v186, v[128:131] offset:12288
	s_mov_b32 s19, -1
	v_lshl_add_u64 v[128:129], v[168:169], 0, s[18:19]
	s_mov_b32 s18, 0xfffc0000
	s_waitcnt lgkmcnt(7)
; __device__ __forceinline__ void partialSM(f32x16& p0, f32x16& p1, float& m_reg, float& mn, float& alpha) {
;     ...
;   for (int r = 1; r < 16; ++r) pmax = fmaxf(pmax, p0[r]);
; #pragma unroll
;   for (int r = 0; r < 16; ++r) pmax = fmaxf(pmax, p1[r]);
;   { auto rr = __builtin_amdgcn_permlane32_swap(__float_as_uint(pmax), __float_as_uint(pmax), false, false);
;     pmax = fmaxf(__uint_as_float(rr[0]), __uint_as_float(rr[1])); }
;   if (__builtin_expect(__all(pmax - m_reg <= THR / SCALE), 1)) { mn = m_reg; alpha = 1.f; }
;   else { mn = fmaxf(m_reg, pmax); alpha = __builtin_amdgcn_exp2f((m_reg - mn) * C); m_reg = mn; }
;   float mnC = -mn * C;
; #pragma unroll
;   for (int r = 0; r < 16; ++r) p0[r] = fmaf(p0[r], C, mnC);
; #pragma unroll
;   for (int r = 0; r < 16; ++r) p1[r] = fmaf(p1[r], C, mnC);
; #pragma unroll
;   for (int r = 0; r < 16; ++r) p0[r] = __builtin_amdgcn_exp2f(p0[r]);
; }
; __device__ __forceinline__ void finishSM(f32x16& p0, f32x16& p1, float alpha, float& l_reg, bf16x8& pa0, bf16x8& pa1, bf16x8& pa2, bf16x8& pa3) {
; #pragma unroll
;   for (int r = 0; r < 16; ++r) p1[r] = __builtin_amdgcn_exp2f(p1[r]);
;   float ps = 0;
; #pragma unroll
;   for (int r = 0; r < 16; ++r) ps += p0[r];
; #pragma unroll
;   for (int r = 0; r < 16; ++r) ps += p1[r];
;   { auto rr = __builtin_amdgcn_permlane32_swap(__float_as_uint(ps), __float_as_uint(ps), false, false);
;     ps = __uint_as_float(rr[0]) + __uint_as_float(rr[1]); }
;   l_reg = l_reg * alpha + ps;
;     ...
;   PK4(p0, 0, pa0); PK4(p0, 8, pa1); PK4(p1, 0, pa2); PK4(p1, 8, pa3);
;     ...
; }
; __device__ __forceinline__ void qkt(f32x16& p0, f32x16& p1, const char* Ks, const bf16x8* qr, const char* qrl, int r32, int hi) {
;   p0 = f32x16{}; p1 = f32x16{};
; #pragma unroll
;   for (int d0 = 0; d0 < 8; ++d0) { int cb = (d0 * 16 + hi * 8) * 2;
;     bf16x8 b0 = *reinterpret_cast<const bf16x8*>(Ks + KSWZ(r32, cb));
;     bf16x8 b1 = *reinterpret_cast<const bf16x8*>(Ks + KSWZ(32 + r32, cb));
;     p0 = __builtin_amdgcn_mfma_f32_32x32x16_bf16(b0, qr[d0], p0, 0, 0, 0);
;     p1 = __builtin_amdgcn_mfma_f32_32x32x16_bf16(b1, qr[d0], p1, 0, 0, 0); }
; #pragma unroll
;   for (int d0 = 8; d0 < 12; ++d0) { int cb = (d0 * 16 + hi * 8) * 2;
;     bf16x8 b0 = *reinterpret_cast<const bf16x8*>(Ks + KSWZ(r32, cb));
;     bf16x8 b1 = *reinterpret_cast<const bf16x8*>(Ks + KSWZ(32 + r32, cb));
	v_mfma_f32_32x32x16_bf16 v[80:95], v[240:243], v[244:247], v[80:95]
	ds_read_b128 v[240:243], v181
	v_lshl_add_u64 v[130:131], v[168:169], 0, s[18:19]
	global_load_dwordx4 v[140:143], v[128:129], off
	global_load_dwordx4 v[136:139], v[128:129], off offset:-256
	global_load_dwordx4 v[144:147], v[130:131], off
	global_load_dwordx4 v[132:135], v[130:131], off offset:-256
	s_movk_i32 s18, 0xe000
	v_lshl_add_u64 v[128:129], v[166:167], 0, s[18:19]
	v_mfma_f32_32x32x16_bf16 v[64:79], v[248:251], v[244:247], v[64:79]
	ds_read_b128 v[248:251], v187 offset:36864
	ds_read_b128 v[244:247], v189 offset:49152
	global_load_dwordx4 v[128:131], v[128:129], off
	v_cvt_pk_bf16_f32 v158, v158, v159
	v_cvt_pk_bf16_f32 v159, v156, v157
	v_permlane32_swap_b32_e32 v211, v212
	v_cvt_pk_bf16_f32 v156, v162, v163
	v_cvt_pk_bf16_f32 v157, v160, v161
	s_waitcnt lgkmcnt(2)
	v_mfma_f32_32x32x16_bf16 v[80:95], v[232:235], v[240:243], v[80:95]
	ds_read_b128 v[232:235], v179
	v_cvt_pk_bf16_f32 v160, v154, v155
	v_cvt_pk_bf16_f32 v161, v152, v153
	v_cvt_pk_bf16_f32 v162, v150, v151
	v_cvt_pk_bf16_f32 v163, v148, v149
	v_add_f32_e32 v211, v211, v212
	v_cvt_pk_bf16_f32 v148, v225, v228
	v_mfma_f32_32x32x16_bf16 v[64:79], v[236:239], v[240:243], v[64:79]
	ds_read_b128 v[236:239], v188 offset:36864
	ds_read_b128 v[240:243], v190 offset:49152
	v_cvt_pk_bf16_f32 v149, v226, v229
	v_cvt_pk_bf16_f32 v150, v227, v230
	v_cvt_pk_bf16_f32 v151, v223, v224
	v_cvt_pk_bf16_f32 v152, v219, v221
	v_cvt_pk_bf16_f32 v153, v220, v222
	v_cvt_pk_bf16_f32 v154, v215, v217
	s_waitcnt lgkmcnt(2)
	v_mfma_f32_32x32x16_bf16 v[80:95], v[248:251], v[232:235], v[80:95]
	ds_read_b128 v[248:251], v177
	v_cvt_pk_bf16_f32 v155, v216, v218
	v_fma_f32 v176, v209, v176, v211
	v_mfma_f32_32x32x16_bf16 v[64:79], v[244:247], v[232:235], v[64:79]
	s_waitcnt lgkmcnt(0)
	v_mfma_f32_32x32x16_bf16 v[80:95], v[236:239], v[248:251], v[80:95]
	v_mfma_f32_32x32x16_bf16 v[64:79], v[240:243], v[248:251], v[64:79]
	s_lshl_b32 s31, s30, 14
	v_add_u32_e32 v180, s31, v178
	ds_read_b64_tr_b16 v[232:233], v180 offset:0
	ds_read_b64_tr_b16 v[234:235], v180 offset:2048
	ds_read_b64_tr_b16 v[236:237], v180 offset:512
	ds_read_b64_tr_b16 v[238:239], v180 offset:2560
	ds_read_b64_tr_b16 v[240:241], v180 offset:1024
	ds_read_b64_tr_b16 v[242:243], v180 offset:3072
	ds_read_b64_tr_b16 v[248:249], v180 offset:1536
	ds_read_b64_tr_b16 v[250:251], v180 offset:3584
	ds_read_b64_tr_b16 v[244:245], v180 offset:4096
	ds_read_b64_tr_b16 v[246:247], v180 offset:6144
	s_nop 3
	v_max3_f32 v194, v80, v81, v82
	v_max3_f32 v195, v64, v65, v66
	v_max3_f32 v194, v194, v83, v84
	v_max3_f32 v195, v195, v67, v68
	s_waitcnt lgkmcnt(6)
	v_mfma_f32_32x32x16_bf16 v[32:47], v[148:151], v[232:235], v[32:47]
	ds_read_b64_tr_b16 v[232:233], v180 offset:4608
	ds_read_b64_tr_b16 v[234:235], v180 offset:6656
	v_max3_f32 v194, v194, v85, v86
	v_max3_f32 v195, v195, v69, v70
	v_max3_f32 v194, v194, v87, v88
	v_max3_f32 v195, v195, v71, v72
	v_mfma_f32_32x32x16_bf16 v[48:63], v[148:151], v[236:239], v[48:63]
	ds_read_b64_tr_b16 v[236:237], v180 offset:5120
	ds_read_b64_tr_b16 v[238:239], v180 offset:7168
	v_max3_f32 v194, v194, v89, v90
	v_max3_f32 v195, v195, v73, v74
	v_max3_f32 v194, v194, v91, v92
	v_max3_f32 v195, v195, v75, v76
	s_waitcnt lgkmcnt(6)
	v_mfma_f32_32x32x16_bf16 v[16:31], v[148:151], v[240:243], v[16:31]
	ds_read_b64_tr_b16 v[240:241], v180 offset:5632
	ds_read_b64_tr_b16 v[242:243], v180 offset:7680
	v_max3_f32 v194, v194, v93, v94
	v_max3_f32 v195, v195, v77, v78
	v_max3_f32 v194, v194, v95, v195
	v_max_f32_e32 v194, v194, v79
	v_mfma_f32_32x32x16_bf16 v[0:15], v[148:151], v[248:251], v[0:15]
	ds_read_b64_tr_b16 v[248:249], v180 offset:8192
	ds_read_b64_tr_b16 v[250:251], v180 offset:10240
	v_mov_b32_e32 v195, v194
	s_nop 1
	v_permlane32_swap_b32_e32 v194, v195
	v_max_f32_e32 v194, v194, v195
	s_waitcnt lgkmcnt(6)
	v_mfma_f32_32x32x16_bf16 v[32:47], v[152:155], v[244:247], v[32:47]
	ds_read_b64_tr_b16 v[244:245], v180 offset:8704
	ds_read_b64_tr_b16 v[246:247], v180 offset:10752
	v_sub_f32_e32 v195, v194, v210
	v_cmp_ge_f32_e32 vcc, s15, v195
	v_mfma_f32_32x32x16_bf16 v[48:63], v[152:155], v[232:235], v[48:63]
	ds_read_b64_tr_b16 v[232:233], v180 offset:9216
	ds_read_b64_tr_b16 v[234:235], v180 offset:11264
	s_cmp_eq_u64 vcc, exec
	s_cselect_b64 s[40:41], -1, 0
	s_cbranch_scc1 .Lattn_fast1
	v_max_f32_e32 v194, v210, v194
	v_sub_f32_e32 v195, v210, v194
	v_mul_f32_e32 v195, 0x3dd53b94, v195
	v_exp_f32_e32 v214, v195
	v_mov_b32_e32 v210, v194
	s_branch .Lattn_join1
